# P1: deferred weight-conversion shared: all WGs take items [3584,7680) (2 per wave) + rope table, the one-unit-fewer WGs take [0,3584)
# speedup vs baseline: 1.0039x; 1.0039x over previous
; __device__ __forceinline__ void p0_deferred(const Ptrs& P, LAS unsigned char* lds, int gw, int NGW, int wave, int lane) {
;     ...
;     tr_loop([&](int it) {
;         int r = it;
;         if (r < I_D) return TrD{P.w1d, P.W1D, nullptr, DFF, D, 0, r}; r -= I_D;
;         if (r < I_IN) return TrD{P.win, P.WIN, P.gma, D, INW, 3, r}; r -= I_IN;
;         if (r < I_OUT) return TrD{P.wout, P.WOUT, nullptr, D, D, 0, r}; r -= I_OUT;
;         if (r < I_GU) return TrD{P.w2g, P.W2GU, P.g2a, D, DFF, 1, r}; r -= I_GU;
;         if (r < I_GU) return TrD{P.w2u, P.W2GU, P.g2a, D, DFF, 2, r}; r -= I_GU;
;         return TrD{P.w2d, P.W2D, nullptr, DFF, D, 0, r};
;     }, gw, NITEMS, NGW, lane, scr);
; __global__ void __launch_bounds__(NTHR, 2) mk_fwd(Args a) {
;     ...
;     {
;         constexpr int NU1 = (M / 256) * (2 * DFF / 256);
;         const int rounds = (NU1 + G - 1) / G, idle0 = NU1 - (rounds - 1) * G;
;         if (idle0 >= G) p0_deferred(P, lds, gw, NGW, wave, lane);
;         else if ((int)blockIdx.x >= idle0) p0_deferred(P, lds, ((int)blockIdx.x - idle0) * NWAVES + wave, (G - idle0) * NWAVES, wave, lane);
.LBB0_106:
	s_lshl_b32 s0, s87, 9
	s_add_u32 s72, s90, 0xc00000
	s_addc_u32 s73, s91, 0
	v_writelane_b32 v254, s0, 41
	s_add_u32 s0, s90, 0x1800000
	s_addc_u32 s1, s91, 0
	v_writelane_b32 v254, s0, 42
	s_nop 1
	v_writelane_b32 v254, s1, 43
	s_add_u32 s0, s90, 0x2500000
	s_addc_u32 s1, s91, 0
	s_add_u32 s94, s90, 0x2b00000
	s_addc_u32 s95, s91, 0
	s_add_u32 s96, s90, 0x1200000
	v_writelane_b32 v254, s0, 44
	s_addc_u32 s97, s91, 0
	s_nop 0
	v_writelane_b32 v254, s1, 45
	s_add_u32 s0, s90, 0x1a00000
	s_addc_u32 s1, s91, 0
	v_writelane_b32 v254, s0, 46
	s_nop 1
	v_writelane_b32 v254, s1, 47
	s_abs_i32 s0, s87
	s_waitcnt vmcnt(4)
	v_cvt_f32_u32_e32 v2, s0
	s_add_i32 s1, s87, 0x5ab
	s_xor_b32 s2, s1, s87
	s_sub_i32 s3, 0, s0
	v_rcp_iflag_f32_e32 v2, v2
	s_ashr_i32 s29, s2, 31
	s_abs_i32 s1, s1
	v_mul_f32_e32 v2, 0x4f7ffffe, v2
	v_cvt_u32_f32_e32 v2, v2
	s_nop 0
	v_readfirstlane_b32 s2, v2
	s_mul_i32 s3, s3, s2
	s_mul_hi_u32 s3, s2, s3
	s_add_i32 s2, s2, s3
	s_mul_hi_u32 s2, s1, s2
	s_mul_i32 s3, s2, s0
	s_sub_i32 s1, s1, s3
	s_add_i32 s4, s2, 1
	s_sub_i32 s3, s1, s0
	s_cmp_ge_u32 s1, s0
	s_cselect_b32 s2, s4, s2
	s_cselect_b32 s1, s3, s1
	s_add_i32 s3, s2, 1
	s_cmp_ge_u32 s1, s0
	s_cselect_b32 s0, s3, s2
	s_xor_b32 s30, s0, s29
	s_sub_i32 s0, s30, s29
	v_writelane_b32 v254, s0, 48
	s_add_i32 s0, s0, -1
	s_mul_i32 s0, s0, s87
	v_writelane_b32 v254, s0, 49
	s_sub_i32 s0, 0x5ac, s0
	s_cmp_le_i32 s87, s0
	s_cselect_b64 s[2:3], -1, 0
	v_writelane_b32 v254, s2, 50
	s_cmp_gt_i32 s87, s0
	s_nop 0
	v_writelane_b32 v254, s3, 51
	v_writelane_b32 v254, s0, 52
	s_mov_b64 s[0:1], -1
	s_mov_b32 s98, 0
	s_cbranch_scc0 .Lp1_gen
	s_movk_i32 s98, 0xe00
.Lp1_gen:
	v_writelane_b32 v254, s30, 53
	v_writelane_b32 v254, s29, 55
	s_nop 0
	v_readlane_b32 s0, v254, 35
	s_add_i32 s0, s0, s98
	s_nop 3
	v_writelane_b32 v254, s0, 35
	s_nop 3
	v_readlane_b32 s0, v254, 35
	s_cmpk_gt_i32 s0, 0x1dff
	v_readlane_b32 s1, v254, 36
	s_cbranch_scc1 .LBB0_221
	v_readlane_b32 s30, v254, 35
	s_mov_b32 s46, 0
	s_mov_b64 s[4:5], 0
	s_cmpk_lt_i32 s30, 0x580
	s_movk_i32 s53, 0x400
	v_readlane_b32 s31, v254, 36
	s_cbranch_scc1 .LBB0_114
	s_cmpk_gt_u32 s30, 0xb7f
	s_cbranch_scc0 .LBB0_115
	s_cmpk_gt_u32 s30, 0xd7f
	s_cbranch_scc0 .LBB0_116
	s_cmpk_gt_u32 s30, 0x12ff
	s_cbranch_scc0 .LBB0_117
	s_cmpk_gt_u32 s30, 0x187f
	s_cbranch_scc0 .LBB0_118
	v_readlane_b32 s20, v254, 3
	v_readlane_b32 s26, v254, 9
	v_readlane_b32 s27, v254, 10
	s_add_i32 s47, s30, 0xffffe780
	s_mov_b64 s[0:1], 0
	v_readlane_b32 s21, v254, 4
	v_readlane_b32 s22, v254, 5
	v_readlane_b32 s23, v254, 6
	v_readlane_b32 s24, v254, 7
	v_readlane_b32 s25, v254, 8
	s_mov_b64 s[2:3], s[26:27]
	s_branch .LBB0_119

; #define LAS __attribute__((address_space(3)))
; __device__ __forceinline__ void p0_deferred(const Ptrs& P, LAS unsigned char* lds, int gw, int NGW, int wave, int lane) {
;     ...
;     {
;         LAS float* fl = (LAS float*)(lds + 12288);
;         if (threadIdx.x < 40) fl[threadIdx.x] = INVF[threadIdx.x];
;         __syncthreads();
.LBB0_221:
	v_readlane_b32 s0, v254, 35
	s_sub_i32 s0, s0, s98
	s_nop 3
	v_writelane_b32 v254, s0, 35
	s_nop 3
	v_cmp_gt_u32_e32 vcc, 40, v0
	s_and_saveexec_b64 s[0:1], vcc
	s_cbranch_execz .LBB0_223
	s_getpc_b64 s[2:3]
	s_add_u32 s2, s2, INVF@rel32@lo+4
	s_addc_u32 s3, s3, INVF@rel32@hi+12
	global_load_dword v2, v163, s[2:3]
	v_add_u32_e32 v3, 0, v163
	s_waitcnt vmcnt(0)
	ds_write_b32 v3, v2 offset:12288

; __device__ __forceinline__ void p0_deferred(const Ptrs& P, LAS unsigned char* lds, int gw, int NGW, int wave, int lane) {
;     ...
;     tr_loop([&](int it) {
;         int r = it;
;         if (r < I_D) return TrD{P.w1d, P.W1D, nullptr, DFF, D, 0, r}; r -= I_D;
;         if (r < I_IN) return TrD{P.win, P.WIN, P.gma, D, INW, 3, r}; r -= I_IN;
;         if (r < I_OUT) return TrD{P.wout, P.WOUT, nullptr, D, D, 0, r}; r -= I_OUT;
;         if (r < I_GU) return TrD{P.w2g, P.W2GU, P.g2a, D, DFF, 1, r}; r -= I_GU;
;         if (r < I_GU) return TrD{P.w2u, P.W2GU, P.g2a, D, DFF, 2, r}; r -= I_GU;
;         return TrD{P.w2d, P.W2D, nullptr, DFF, D, 0, r};
;     }, gw, NITEMS, NGW, lane, scr);
; __global__ void __launch_bounds__(NTHR, 2) mk_fwd(Args a) {
;     ...
;     {
;         constexpr int NU1 = (M / 256) * (2 * DFF / 256);
;         const int rounds = (NU1 + G - 1) / G, idle0 = NU1 - (rounds - 1) * G;
;         if (idle0 >= G) p0_deferred(P, lds, gw, NGW, wave, lane);
;         else if ((int)blockIdx.x >= idle0) p0_deferred(P, lds, ((int)blockIdx.x - idle0) * NWAVES + wave, (G - idle0) * NWAVES, wave, lane);
.LBB0_226:
	s_or_b64 exec, exec, s[0:1]
	s_cmp_eq_u32 s98, 0
	s_cbranch_scc1 .LBB0_349
	s_lshl_b32 s0, s87, 9
	s_add_u32 s72, s90, 0xc00000
	s_addc_u32 s73, s91, 0
	v_writelane_b32 v254, s0, 41
	s_add_u32 s0, s90, 0x1800000
	s_addc_u32 s1, s91, 0
	v_writelane_b32 v254, s0, 42
	s_nop 1
	v_writelane_b32 v254, s1, 43
	s_add_u32 s0, s90, 0x2500000
	s_addc_u32 s1, s91, 0
	s_add_u32 s94, s90, 0x2b00000
	s_addc_u32 s95, s91, 0
	s_add_u32 s96, s90, 0x1200000
	v_writelane_b32 v254, s0, 44
	s_addc_u32 s97, s91, 0
	s_nop 0
	v_writelane_b32 v254, s1, 45
	s_add_u32 s0, s90, 0x1a00000
	s_addc_u32 s1, s91, 0
	v_writelane_b32 v254, s0, 46
	s_nop 1
	v_writelane_b32 v254, s1, 47
	s_abs_i32 s0, s87
	s_waitcnt vmcnt(4)
	v_cvt_f32_u32_e32 v2, s0
	s_add_i32 s1, s87, 0x5ab
	s_xor_b32 s2, s1, s87
	s_sub_i32 s3, 0, s0
	v_rcp_iflag_f32_e32 v2, v2
	s_ashr_i32 s29, s2, 31
	s_abs_i32 s1, s1
	v_mul_f32_e32 v2, 0x4f7ffffe, v2
	v_cvt_u32_f32_e32 v2, v2
	s_nop 0
	v_readfirstlane_b32 s2, v2
	s_mul_i32 s3, s3, s2
	s_mul_hi_u32 s3, s2, s3
	s_add_i32 s2, s2, s3
	s_mul_hi_u32 s2, s1, s2
	s_mul_i32 s3, s2, s0
	s_sub_i32 s1, s1, s3
	s_add_i32 s4, s2, 1
	s_sub_i32 s3, s1, s0
	s_cmp_ge_u32 s1, s0
	s_cselect_b32 s2, s4, s2
	s_cselect_b32 s1, s3, s1
	s_add_i32 s3, s2, 1
	s_cmp_ge_u32 s1, s0
	s_cselect_b32 s0, s3, s2
	s_xor_b32 s30, s0, s29
	s_sub_i32 s0, s30, s29
	v_writelane_b32 v254, s0, 48
	s_add_i32 s0, s0, -1
	s_mul_i32 s0, s0, s87
	v_writelane_b32 v254, s0, 49
	s_sub_i32 s0, 0x5ac, s0
	s_cmp_le_i32 s87, s0
	s_cselect_b64 s[2:3], -1, 0
	v_writelane_b32 v254, s2, 50
	s_cmp_gt_i32 s87, s0
	s_nop 0
	v_writelane_b32 v254, s3, 51
	v_writelane_b32 v254, s0, 52
	v_readlane_b32 s0, v254, 52
	s_cmp_lt_i32 s86, s0
	s_cbranch_scc1 .LBB0_349
	v_readlane_b32 s0, v254, 52
	s_sub_i32 s0, s86, s0
	s_lshl_b32 s50, s0, 3
	v_readlane_b32 s0, v254, 34
	s_add_i32 s68, s50, s0
	s_cmpk_gt_u32 s68, 0xdff
	s_cbranch_scc1 .LBB0_343
	s_mov_b32 s3, 0
	s_mov_b64 s[6:7], 0
	s_cmpk_lt_u32 s68, 0x580
	s_cbranch_scc1 .LBB0_236
	s_cmpk_gt_u32 s68, 0xb7f
	s_cbranch_scc0 .LBB0_237
	s_cmpk_gt_u32 s68, 0xd7f
	s_cbranch_scc0 .LBB0_238
	s_cmpk_gt_u32 s68, 0x12ff
	s_cbranch_scc0 .LBB0_239
	s_cmpk_gt_u32 s68, 0x187f
	s_cbranch_scc0 .LBB0_240
	v_readlane_b32 s20, v254, 3
	v_readlane_b32 s26, v254, 9
	v_readlane_b32 s27, v254, 10
	s_add_i32 s47, s68, 0xffffe780
	s_mov_b64 s[0:1], 0
	v_readlane_b32 s21, v254, 4
	v_readlane_b32 s22, v254, 5
	v_readlane_b32 s23, v254, 6
	v_readlane_b32 s24, v254, 7
	v_readlane_b32 s25, v254, 8
	s_mov_b64 s[4:5], s[26:27]
	s_branch .LBB0_241

; #define GAS __attribute__((address_space(1)))
; #define LAS __attribute__((address_space(3)))
; #define LDS_WAIT() asm volatile("s_waitcnt lgkmcnt(0)" ::: "memory")
; __device__ __forceinline__ unsigned pk2(float lo, float hi) { return f2bf(lo) | (f2bf(hi) << 16); }
; __device__ __forceinline__ void tr_finish(const TrD& d, int lane, const f32x4 (&v)[8], const float (&gg)[8], LAS float* scr) {
;     ...
;         for (int i = 0; i < 8; ++i) { LAS float* dd = scr + (8 * i + row8) * 33 + 4 * c4; dd[0] = v[i][0] * gg[i]; dd[1] = v[i][1] * gg[i]; dd[2] = v[i][2] * gg[i]; dd[3] = v[i][3] * gg[i]; }
;     }
;     LDS_WAIT(); asm volatile("" ::: "memory");
;     const int c = lane & 7;
; #pragma unroll
;     for (int j = 0; j < 4; ++j) { const int n = (lane >> 3) + 8 * j; const LAS float* sp = scr + (8 * c) * 33 + n;
;         v4u o; o.x = pk2(sp[0 * 33], sp[1 * 33]); o.y = pk2(sp[2 * 33], sp[3 * 33]); o.z = pk2(sp[4 * 33], sp[5 * 33]); o.w = pk2(sp[6 * 33], sp[7 * 33]);
;         const int orow = mode == 3 ? win_perm(n0 + n) : rbase + n;
;         *(GAS v4u*)(d.WT + (size_t)orow * K + k0 + 8 * c) = o; }
;     LDS_WAIT(); asm volatile("" ::: "memory");
; }
; template <class DescFn>
; __device__ __forceinline__ void tr_loop(DescFn desc, int first, int nitems, int stride, int lane, LAS float* scr) {
;     ...
;         { const int itn = it + stride; const bool more = itn < nitems; d1 = desc(more ? itn : it); tr_load(d1, lane, v1, g1); __builtin_amdgcn_sched_barrier(0); tr_finish(d0, lane, v0, g0, scr); if (!more) break; it = itn; }
;         { const int itn = it + stride; const bool more = itn < nitems; d0 = desc(more ? itn : it); tr_load(d0, lane, v0, g0); __builtin_amdgcn_sched_barrier(0); tr_finish(d1, lane, v1, g1, scr); if (!more) break; it = itn; }
.LBB0_254:
	s_waitcnt lgkmcnt(3)
	v_bfe_u32 v43, v41, 16, 1
	v_add3_u32 v41, v41, v43, s57
	v_bfe_u32 v43, v40, 16, 1
	v_add3_u32 v40, v40, v43, s57
	v_lshrrev_b32_e32 v40, 16, v40
	v_and_or_b32 v44, v41, s58, v40
	s_waitcnt lgkmcnt(2)
	v_bfe_u32 v40, v39, 16, 1
	v_add3_u32 v39, v39, v40, s57
	v_bfe_u32 v40, v38, 16, 1
	v_add3_u32 v38, v38, v40, s57
	v_lshrrev_b32_e32 v38, 16, v38
	v_and_or_b32 v45, v39, s58, v38
	s_waitcnt lgkmcnt(1)
	v_bfe_u32 v38, v37, 16, 1
	v_add3_u32 v37, v37, v38, s57
	v_bfe_u32 v38, v36, 16, 1
	v_add3_u32 v36, v36, v38, s57
	v_lshrrev_b32_e32 v36, 16, v36
	v_and_or_b32 v46, v37, s58, v36
	s_waitcnt lgkmcnt(0)
	v_bfe_u32 v36, v35, 16, 1
	v_add3_u32 v35, v35, v36, s57
	v_bfe_u32 v36, v34, 16, 1
	v_add3_u32 v34, v34, v36, s57
	v_lshrrev_b32_e32 v34, 16, v34
	v_and_or_b32 v47, v35, s58, v34
	v_ashrrev_i32_e32 v34, 31, v42
	s_waitcnt vmcnt(11)
	v_cndmask_b32_e64 v88, v72, 1.0, s[2:3]
	s_waitcnt vmcnt(10)
	v_cndmask_b32_e64 v86, v73, 1.0, s[2:3]
	s_waitcnt vmcnt(9)
	v_cndmask_b32_e64 v84, v103, 1.0, s[2:3]
	s_waitcnt vmcnt(8)
	v_cndmask_b32_e64 v82, v104, 1.0, s[2:3]
	s_waitcnt vmcnt(7)
	v_cndmask_b32_e64 v80, v105, 1.0, s[2:3]
	s_waitcnt vmcnt(5)
	v_cndmask_b32_e64 v78, v106, 1.0, s[2:3]
	s_waitcnt vmcnt(4)
	v_cndmask_b32_e64 v76, v107, 1.0, s[2:3]
	s_waitcnt vmcnt(3)
	v_cndmask_b32_e64 v74, v108, 1.0, s[2:3]
	v_mul_lo_u32 v36, s29, v42
	v_mul_lo_u32 v37, s28, v34
	v_mad_u64_u32 v[34:35], s[2:3], s28, v42, 0
	v_add3_u32 v35, v35, v37, v36
	v_lshl_add_u64 v[34:35], v[34:35], 1, s[30:31]
	v_lshl_add_u64 v[34:35], s[34:35], 1, v[34:35]
	v_mov_b32_e32 v71, v69
	v_lshl_add_u64 v[34:35], v[34:35], 0, v[70:71]
	global_store_dwordx4 v[34:35], v[44:47], off
	s_waitcnt lgkmcnt(0)
	s_add_i32 s59, s59, s53
	s_add_i32 s2, s48, s59
	s_cmpk_gt_i32 s2, 0xdff
	s_cselect_b64 s[4:5], -1, 0

; template <class DescFn>
; __device__ __forceinline__ void tr_loop(DescFn desc, int first, int nitems, int stride, int lane, LAS float* scr) {
;     ...
;         { const int itn = it + stride; const bool more = itn < nitems; d1 = desc(more ? itn : it); tr_load(d1, lane, v1, g1); __builtin_amdgcn_sched_barrier(0); tr_finish(d0, lane, v0, g0, scr); if (!more) break; it = itn; }
;         { const int itn = it + stride; const bool more = itn < nitems; d0 = desc(more ? itn : it); tr_load(d0, lane, v0, g0); __builtin_amdgcn_sched_barrier(0); tr_finish(d1, lane, v1, g1, scr); if (!more) break; it = itn; }
; __device__ __forceinline__ void p0_deferred(const Ptrs& P, LAS unsigned char* lds, int gw, int NGW, int wave, int lane) {
;     ...
;     tr_loop([&](int it) {
;         int r = it;
;         if (r < I_D) return TrD{P.w1d, P.W1D, nullptr, DFF, D, 0, r}; r -= I_D;
;         if (r < I_IN) return TrD{P.win, P.WIN, P.gma, D, INW, 3, r}; r -= I_IN;
;         if (r < I_OUT) return TrD{P.wout, P.WOUT, nullptr, D, D, 0, r}; r -= I_OUT;
;         if (r < I_GU) return TrD{P.w2g, P.W2GU, P.g2a, D, DFF, 1, r}; r -= I_GU;
;         if (r < I_GU) return TrD{P.w2u, P.W2GU, P.g2a, D, DFF, 2, r}; r -= I_GU;
;         return TrD{P.w2d, P.W2D, nullptr, DFF, D, 0, r};
;     }, gw, NITEMS, NGW, lane, scr);
.LBB0_256:
	s_add_i32 s4, s52, s59
	s_add_i32 s63, s55, s59
	s_cmpk_lt_i32 s63, 0xe00
	s_cselect_b64 s[40:41], -1, 0
	s_and_b64 s[2:3], s[40:41], exec
	s_cselect_b32 s35, s63, s4
	s_cmpk_lt_i32 s35, 0x580
	s_mov_b64 s[6:7], -1
	s_cbranch_scc1 .LBB0_263
	s_cmpk_gt_u32 s35, 0xb7f
	s_cbranch_scc0 .LBB0_264
	s_cmpk_gt_u32 s35, 0xd7f
	s_cbranch_scc0 .LBB0_265
	s_cmpk_gt_u32 s35, 0x12ff
	s_cbranch_scc0 .LBB0_266
	s_cmpk_gt_u32 s35, 0x187f
	s_mov_b64 s[38:39], -1
	s_cbranch_scc0 .LBB0_308
	v_readlane_b32 s20, v254, 3
	v_readlane_b32 s26, v254, 9
	v_readlane_b32 s27, v254, 10
	s_add_i32 s34, s35, 0xffffe780
	s_mov_b64 s[44:45], 0
	v_readlane_b32 s21, v254, 4
	v_readlane_b32 s22, v254, 5
	v_readlane_b32 s23, v254, 6
	v_readlane_b32 s24, v254, 7
	v_readlane_b32 s25, v254, 8
	s_mov_b64 s[4:5], s[26:27]
	s_cbranch_execz .LBB0_309
	v_readlane_b32 s30, v254, 44
	s_movk_i32 s64, 0x400
	s_mov_b64 s[28:29], 0xb00
	s_mov_b32 s61, 0
	v_readlane_b32 s31, v254, 45
	s_cbranch_execz .LBB0_267
	s_branch .LBB0_268

; #define GAS __attribute__((address_space(1)))
; #define LAS __attribute__((address_space(3)))
; #define LDS_WAIT() asm volatile("s_waitcnt lgkmcnt(0)" ::: "memory")
; __device__ __forceinline__ unsigned pk2(float lo, float hi) { return f2bf(lo) | (f2bf(hi) << 16); }
; __device__ __forceinline__ void tr_finish(const TrD& d, int lane, const f32x4 (&v)[8], const float (&gg)[8], LAS float* scr) {
;     ...
;         for (int i = 0; i < 8; ++i) { LAS float* dd = scr + (8 * i + row8) * 33 + 4 * c4; dd[0] = v[i][0] * gg[i]; dd[1] = v[i][1] * gg[i]; dd[2] = v[i][2] * gg[i]; dd[3] = v[i][3] * gg[i]; }
;     }
;     LDS_WAIT(); asm volatile("" ::: "memory");
;     const int c = lane & 7;
; #pragma unroll
;     for (int j = 0; j < 4; ++j) { const int n = (lane >> 3) + 8 * j; const LAS float* sp = scr + (8 * c) * 33 + n;
;         v4u o; o.x = pk2(sp[0 * 33], sp[1 * 33]); o.y = pk2(sp[2 * 33], sp[3 * 33]); o.z = pk2(sp[4 * 33], sp[5 * 33]); o.w = pk2(sp[6 * 33], sp[7 * 33]);
;         const int orow = mode == 3 ? win_perm(n0 + n) : rbase + n;
;         *(GAS v4u*)(d.WT + (size_t)orow * K + k0 + 8 * c) = o; }
;     LDS_WAIT(); asm volatile("" ::: "memory");
; }
; template <class DescFn>
; __device__ __forceinline__ void tr_loop(DescFn desc, int first, int nitems, int stride, int lane, LAS float* scr) {
;     ...
;         { const int itn = it + stride; const bool more = itn < nitems; d1 = desc(more ? itn : it); tr_load(d1, lane, v1, g1); __builtin_amdgcn_sched_barrier(0); tr_finish(d0, lane, v0, g0, scr); if (!more) break; it = itn; }
;         { const int itn = it + stride; const bool more = itn < nitems; d0 = desc(more ? itn : it); tr_load(d0, lane, v0, g0); __builtin_amdgcn_sched_barrier(0); tr_finish(d1, lane, v1, g1, scr); if (!more) break; it = itn; }
.LBB0_297:
	s_waitcnt lgkmcnt(3)
	v_bfe_u32 v11, v9, 16, 1
	v_add3_u32 v9, v9, v11, s57
	v_bfe_u32 v11, v8, 16, 1
	v_add3_u32 v8, v8, v11, s57
	v_lshrrev_b32_e32 v8, 16, v8
	v_and_or_b32 v12, v9, s58, v8
	s_waitcnt lgkmcnt(2)
	v_bfe_u32 v8, v7, 16, 1
	v_add3_u32 v7, v7, v8, s57
	v_bfe_u32 v8, v6, 16, 1
	v_add3_u32 v6, v6, v8, s57
	v_lshrrev_b32_e32 v6, 16, v6
	v_and_or_b32 v13, v7, s58, v6
	s_waitcnt lgkmcnt(1)
	v_bfe_u32 v6, v5, 16, 1
	v_add3_u32 v5, v5, v6, s57
	v_bfe_u32 v6, v4, 16, 1
	v_add3_u32 v4, v4, v6, s57
	v_lshrrev_b32_e32 v4, 16, v4
	v_and_or_b32 v14, v5, s58, v4
	s_waitcnt lgkmcnt(0)
	v_bfe_u32 v4, v3, 16, 1
	v_add3_u32 v3, v3, v4, s57
	v_bfe_u32 v4, v2, 16, 1
	v_add3_u32 v2, v2, v4, s57
	v_lshrrev_b32_e32 v2, 16, v2
	v_and_or_b32 v15, v3, s58, v2
	v_ashrrev_i32_e32 v2, 31, v10
	v_mul_lo_u32 v4, s1, v10
	v_mul_lo_u32 v5, s0, v2
	v_mad_u64_u32 v[2:3], s[0:1], s0, v10, 0
	v_add3_u32 v3, v3, v5, v4
	v_lshl_add_u64 v[2:3], v[2:3], 1, s[70:71]
	v_lshl_add_u64 v[2:3], s[44:45], 1, v[2:3]
	v_mov_b32_e32 v71, v69
	v_lshl_add_u64 v[2:3], v[2:3], 0, v[70:71]
	global_store_dwordx4 v[2:3], v[12:15], off
	s_waitcnt lgkmcnt(0)
	s_andn2_b64 vcc, exec, s[40:41]
	s_mov_b64 s[4:5], -1
	s_cbranch_vccnz .LBB0_255
	s_xor_b64 s[40:41], s[42:43], -1
	s_add_i32 s0, s54, s59
	s_cmpk_lt_i32 s0, 0xe00
	s_cselect_b32 s47, s0, s63
	s_cmpk_lt_i32 s47, 0x580
	s_cbranch_scc1 .LBB0_305
	s_cmpk_gt_u32 s47, 0xb7f
	s_cbranch_scc0 .LBB0_306
	s_cmpk_gt_u32 s47, 0xd7f
	s_cbranch_scc0 .LBB0_307
	s_cmpk_gt_u32 s47, 0x12ff
	s_cbranch_scc0 .LBB0_310
	s_cmpk_gt_u32 s47, 0x187f
	s_cbranch_scc0 .LBB0_341
	v_readlane_b32 s20, v254, 3
	v_readlane_b32 s26, v254, 9
	v_readlane_b32 s27, v254, 10
	s_add_i32 s37, s47, 0xffffe780
	s_mov_b64 s[6:7], 0
	v_readlane_b32 s21, v254, 4
	v_readlane_b32 s22, v254, 5
	v_readlane_b32 s23, v254, 6
	v_readlane_b32 s24, v254, 7
	v_readlane_b32 s25, v254, 8
	s_mov_b64 s[4:5], s[26:27]
	s_cbranch_execz .LBB0_342
	v_readlane_b32 s70, v254, 44
	s_movk_i32 s60, 0x400
	s_mov_b64 s[0:1], 0xb00
	s_mov_b32 s46, 0
	v_readlane_b32 s71, v254, 45
	s_cbranch_execz .LBB0_311
	s_branch .LBB0_312

; #define LAS __attribute__((address_space(3)))
; __device__ __forceinline__ void p0_deferred(const Ptrs& P, LAS unsigned char* lds, int gw, int NGW, int wave, int lane) {
;     ...
;     {
;         LAS float* fl = (LAS float*)(lds + 12288);
;         if (threadIdx.x < 40) fl[threadIdx.x] = INVF[threadIdx.x];
;         __syncthreads();
;         for (int idx = gw * 64 + lane; idx < SEQ * 40; idx += NGW * 64) {
;             const int pos = idx / 40, f = idx % 40;
;             const float ang = (float)pos * fl[f];
;             const double rev = (double)ang * 0.15915494309189535;
;             const float fr = (float)(rev - rint(rev));
;             P.TAB[idx] = pg8::pk_h2(__builtin_amdgcn_cosf(fr), __builtin_amdgcn_sinf(fr));
;         }
;     }
.LBB0_343:
	s_branch .LBB0_349
